# gMLP spatial-gate item (both G==256 instances): the 8 weight fragments are loaded before the barrier and LDS fragments batched, instead of 8 serialized load-wait-MFMA steps
# baseline (speedup 1.0000x reference)
.LBB0_1317:
	v_mov_b32_e32 v44, v173
	v_mov_b64_e32 v[2:3], s[50:51]
	v_ashrrev_i32_e32 v45, 2, v44
	v_add_u32_e32 v0, s4, v45
	s_or_b32 s5, s5, s38
	v_mad_i64_i32 v[2:3], s[0:1], v0, s84, v[2:3]
	v_lshlrev_b32_e32 v0, 4, v44
	s_lshl_b32 s54, s5, 7
	v_and_b32_e32 v46, 48, v0
	v_lshl_add_u64 v[2:3], v[2:3], 0, s[54:55]
	v_lshlrev_b32_e32 v0, 1, v46
	v_lshl_add_u64 v[6:7], v[2:3], 0, v[0:1]
	v_and_b32_e32 v8, 64, v189
	global_load_dwordx4 v[2:5], v[6:7], off offset:1040
	v_add_u32_e32 v47, 64, v8
	global_load_dwordx4 v[6:9], v[6:7], off offset:1024
	v_xor_b32_e32 v0, 1, v189
	v_cmp_lt_i32_e32 vcc, v0, v47
	v_readlane_b32 s0, v254, 61
	s_or_b32 s0, s5, s0
	v_cndmask_b32_e32 v0, v189, v0, vcc
	v_lshlrev_b32_e32 v48, 2, v0
	s_lshl_b32 s54, s0, 7
	s_waitcnt vmcnt(0)
	v_and_b32_e32 v10, 0xffff0000, v2
	v_lshlrev_b32_e32 v11, 16, v2
	v_lshlrev_b32_e32 v30, 16, v6
	v_and_b32_e32 v31, 0xffff0000, v6
	v_mul_f32_e32 v6, 0x3d372713, v30
	v_mul_f32_e32 v6, v6, v30
	v_mov_b32_e32 v32, v30
	v_fmac_f32_e32 v32, v6, v32
	v_mul_f32_e32 v6, 0xbfcc422a, v32
	v_mul_f32_e32 v32, 0x3d372713, v31
	v_mul_f32_e32 v32, v32, v31
	v_mov_b32_e32 v33, v31
	v_fmac_f32_e32 v33, v32, v33
	v_mul_f32_e32 v6, 0x3fb8aa3b, v6
	v_mul_f32_e32 v32, 0xbfcc422a, v33
	v_exp_f32_e32 v6, v6
	v_mul_f32_e32 v32, 0x3fb8aa3b, v32
	v_exp_f32_e32 v32, v32
	v_and_b32_e32 v33, 0xffff0000, v7
	v_add_f32_e32 v0, 1.0, v6
	v_rcp_f32_e32 v6, v0
	v_add_f32_e32 v0, 1.0, v32
	v_lshlrev_b32_e32 v32, 16, v7
	v_mul_f32_e32 v7, 0x3d372713, v32
	v_mul_f32_e32 v7, v7, v32
	v_mov_b32_e32 v34, v32
	v_fmac_f32_e32 v34, v7, v34
	v_mul_f32_e32 v7, 0xbfcc422a, v34
	v_mul_f32_e32 v7, 0x3fb8aa3b, v7
	v_exp_f32_e32 v34, v7
	v_mul_f32_e32 v7, 0x3d372713, v33
	v_mul_f32_e32 v7, v7, v33
	v_mov_b32_e32 v35, v33
	v_fmac_f32_e32 v35, v7, v35
	v_mul_f32_e32 v7, 0xbfcc422a, v35
	v_mul_f32_e32 v7, 0x3fb8aa3b, v7
	v_exp_f32_e32 v35, v7
	v_rcp_f32_e32 v7, v0
	v_add_f32_e32 v0, 1.0, v34
	v_rcp_f32_e32 v34, v0
	v_add_f32_e32 v0, 1.0, v35
	v_rcp_f32_e32 v35, v0
	v_pk_mul_f32 v[36:37], v[6:7], v[30:31]
	v_lshlrev_b32_e32 v38, 16, v8
	v_add_f32_e32 v0, 0, v36
	v_add_f32_e32 v0, v37, v0
	v_pk_mul_f32 v[36:37], v[34:35], v[32:33]
	v_and_b32_e32 v39, 0xffff0000, v8
	v_mul_f32_e32 v8, 0x3d372713, v38
	v_add_f32_e32 v0, v36, v0
	v_mul_f32_e32 v8, v8, v38
	v_mov_b32_e32 v36, v38
	v_fmac_f32_e32 v36, v8, v36
	v_mul_f32_e32 v8, 0xbfcc422a, v36
	v_mul_f32_e32 v36, 0x3d372713, v39
	v_mul_f32_e32 v36, v36, v39
	v_mov_b32_e32 v40, v39
	v_fmac_f32_e32 v40, v36, v40
	v_mul_f32_e32 v36, 0xbfcc422a, v40
	v_mul_f32_e32 v36, 0x3fb8aa3b, v36
	v_exp_f32_e32 v36, v36
	v_add_f32_e32 v0, v37, v0
	v_and_b32_e32 v37, 0xffff0000, v9
	v_mov_b32_e32 v42, v37
	v_add_f32_e32 v40, 1.0, v36
	v_lshlrev_b32_e32 v36, 16, v9
	v_mul_f32_e32 v9, 0x3d372713, v36
	v_mul_f32_e32 v9, v9, v36
	v_mov_b32_e32 v41, v36
	v_fmac_f32_e32 v41, v9, v41
	v_mul_f32_e32 v9, 0xbfcc422a, v41
	v_mul_f32_e32 v9, 0x3fb8aa3b, v9
	v_exp_f32_e32 v41, v9
	v_mul_f32_e32 v9, 0x3d372713, v37
	v_mul_f32_e32 v9, v9, v37
	v_mul_f32_e32 v14, 0x3d372713, v11
	v_mul_f32_e32 v16, 0x3d372713, v10
	v_mul_f32_e32 v8, 0x3fb8aa3b, v8
	v_fmac_f32_e32 v42, v9, v42
	v_and_b32_e32 v2, 0xffff0000, v3
	v_lshlrev_b32_e32 v3, 16, v3
	v_mov_b32_e32 v15, v11
	v_mov_b32_e32 v17, v10
	v_mul_f32_e32 v14, v14, v11
	v_mul_f32_e32 v16, v16, v10
	v_exp_f32_e32 v8, v8
	v_mul_f32_e32 v9, 0xbfcc422a, v42
	v_mul_f32_e32 v18, 0x3d372713, v3
	v_mul_f32_e32 v20, 0x3d372713, v2
	v_fmac_f32_e32 v15, v14, v15
	v_fmac_f32_e32 v17, v16, v17
	v_mul_f32_e32 v9, 0x3fb8aa3b, v9
	v_and_b32_e32 v12, 0xffff0000, v4
	v_lshlrev_b32_e32 v13, 16, v4
	v_mov_b32_e32 v19, v3
	v_mov_b32_e32 v21, v2
	v_mul_f32_e32 v18, v18, v3
	v_mul_f32_e32 v20, v20, v2
	v_mul_f32_e32 v14, 0xbfcc422a, v15
	v_mul_f32_e32 v15, 0xbfcc422a, v17
	v_exp_f32_e32 v42, v9
	v_mul_f32_e32 v22, 0x3d372713, v13
	v_mul_f32_e32 v24, 0x3d372713, v12
	v_fmac_f32_e32 v19, v18, v19
	v_fmac_f32_e32 v21, v20, v21
	v_mul_f32_e32 v14, 0x3fb8aa3b, v14
	v_mul_f32_e32 v15, 0x3fb8aa3b, v15
	v_and_b32_e32 v4, 0xffff0000, v5
	v_lshlrev_b32_e32 v5, 16, v5
	v_mov_b32_e32 v23, v13
	v_mov_b32_e32 v25, v12
	v_mul_f32_e32 v22, v22, v13
	v_mul_f32_e32 v24, v24, v12
	v_mul_f32_e32 v16, 0xbfcc422a, v19
	v_mul_f32_e32 v17, 0xbfcc422a, v21
	v_exp_f32_e32 v14, v14
	v_exp_f32_e32 v15, v15
	v_add_f32_e32 v8, 1.0, v8
	v_mul_f32_e32 v26, 0x3d372713, v5
	v_mul_f32_e32 v28, 0x3d372713, v4
	v_fmac_f32_e32 v23, v22, v23
	v_fmac_f32_e32 v25, v24, v25
	v_mul_f32_e32 v16, 0x3fb8aa3b, v16
	v_mul_f32_e32 v17, 0x3fb8aa3b, v17
	v_rcp_f32_e32 v8, v8
	v_rcp_f32_e32 v9, v40
	v_mov_b32_e32 v27, v5
	v_mov_b32_e32 v29, v4
	v_mul_f32_e32 v26, v26, v5
	v_mul_f32_e32 v28, v28, v4
	v_mul_f32_e32 v18, 0xbfcc422a, v23
	v_mul_f32_e32 v19, 0xbfcc422a, v25
	v_exp_f32_e32 v16, v16
	v_exp_f32_e32 v17, v17
	v_add_f32_e32 v40, 1.0, v41
	v_add_f32_e32 v41, 1.0, v42
	v_fmac_f32_e32 v27, v26, v27
	v_fmac_f32_e32 v29, v28, v29
	v_mul_f32_e32 v18, 0x3fb8aa3b, v18
	v_mul_f32_e32 v19, 0x3fb8aa3b, v19
	v_rcp_f32_e32 v40, v40
	v_rcp_f32_e32 v41, v41
	v_mul_f32_e32 v20, 0xbfcc422a, v27
	v_mul_f32_e32 v21, 0xbfcc422a, v29
	v_exp_f32_e32 v18, v18
	v_exp_f32_e32 v19, v19
	v_add_f32_e32 v14, 1.0, v14
	v_add_f32_e32 v22, 1.0, v15
	v_mul_f32_e32 v20, 0x3fb8aa3b, v20
	v_mul_f32_e32 v21, 0x3fb8aa3b, v21
	v_rcp_f32_e32 v15, v14
	v_rcp_f32_e32 v14, v22
	v_pk_mul_f32 v[42:43], v[8:9], v[38:39]
	v_exp_f32_e32 v20, v20
	v_exp_f32_e32 v21, v21
	v_add_f32_e32 v16, 1.0, v16
	v_add_f32_e32 v23, 1.0, v17
	v_add_f32_e32 v0, v42, v0
	v_rcp_f32_e32 v17, v16
	v_rcp_f32_e32 v16, v23
	v_add_f32_e32 v0, v43, v0
	v_pk_mul_f32 v[42:43], v[40:41], v[36:37]
	v_add_f32_e32 v18, 1.0, v18
	v_add_f32_e32 v24, 1.0, v19
	v_add_f32_e32 v0, v42, v0
	v_rcp_f32_e32 v19, v18
	v_rcp_f32_e32 v18, v24
	v_pk_mul_f32 v[22:23], v[14:15], v[10:11]
	v_add_f32_e32 v0, v43, v0
	v_add_f32_e32 v20, 1.0, v20
	v_add_f32_e32 v25, 1.0, v21
	v_add_f32_e32 v0, v23, v0
	v_rcp_f32_e32 v21, v20
	v_rcp_f32_e32 v20, v25
	v_pk_mul_f32 v[24:25], v[16:17], v[2:3]
	v_add_f32_e32 v0, v22, v0
	v_add_f32_e32 v0, v25, v0
	v_pk_mul_f32 v[26:27], v[18:19], v[12:13]
	v_add_f32_e32 v0, v24, v0
	v_add_f32_e32 v0, v27, v0
	v_pk_mul_f32 v[28:29], v[20:21], v[4:5]
	v_add_f32_e32 v0, v26, v0
	v_add_f32_e32 v0, v29, v0
	v_add_f32_e32 v0, v28, v0
	ds_bpermute_b32 v22, v48, v0
	v_xor_b32_e32 v23, 2, v189
	v_cmp_lt_i32_e32 vcc, v23, v47
	s_waitcnt lgkmcnt(0)
	v_add_f32_e32 v0, v0, v22
	v_cndmask_b32_e32 v23, v189, v23, vcc
	v_lshlrev_b32_e32 v42, 2, v23
	ds_bpermute_b32 v22, v42, v0
	s_waitcnt lgkmcnt(0)
	v_add_f32_e32 v0, v0, v22
	v_mul_f32_e32 v0, 0x3c800000, v0
	v_pk_fma_f32 v[6:7], v[6:7], v[30:31], v[0:1] op_sel_hi:[1,1,0] neg_lo:[0,0,1] neg_hi:[0,0,1]
	v_pk_fma_f32 v[24:25], v[34:35], v[32:33], v[0:1] op_sel_hi:[1,1,0] neg_lo:[0,0,1] neg_hi:[0,0,1]
	v_pk_mul_f32 v[22:23], v[6:7], v[6:7]
	v_pk_mul_f32 v[26:27], v[24:25], v[24:25]
	v_pk_fma_f32 v[8:9], v[8:9], v[38:39], v[0:1] op_sel_hi:[1,1,0] neg_lo:[0,0,1] neg_hi:[0,0,1]
	v_pk_fma_f32 v[30:31], v[40:41], v[36:37], v[0:1] op_sel_hi:[1,1,0] neg_lo:[0,0,1] neg_hi:[0,0,1]
	v_pk_fma_f32 v[12:13], v[18:19], v[12:13], v[0:1] op_sel_hi:[1,1,0] neg_lo:[0,0,1] neg_hi:[0,0,1]
	v_pk_fma_f32 v[4:5], v[20:21], v[4:5], v[0:1] op_sel_hi:[1,1,0] neg_lo:[0,0,1] neg_hi:[0,0,1]
	v_pk_fma_f32 v[10:11], v[14:15], v[10:11], v[0:1] op_sel_hi:[1,1,0] neg_lo:[0,0,1] neg_hi:[0,0,1]
	v_pk_fma_f32 v[2:3], v[16:17], v[2:3], v[0:1] op_sel_hi:[1,1,0] neg_lo:[0,0,1] neg_hi:[0,0,1]
	v_add_f32_e32 v0, v22, v23
	v_add_f32_e32 v0, v26, v0
	v_pk_mul_f32 v[28:29], v[8:9], v[8:9]
	v_add_f32_e32 v0, v27, v0
	v_add_f32_e32 v0, v28, v0
	v_pk_mul_f32 v[32:33], v[30:31], v[30:31]
	v_add_f32_e32 v0, v29, v0
	v_add_f32_e32 v0, v32, v0
	v_pk_mul_f32 v[14:15], v[10:11], v[10:11]
	v_add_f32_e32 v0, v33, v0
	v_add_f32_e32 v0, v15, v0
	v_pk_mul_f32 v[16:17], v[2:3], v[2:3]
	v_add_f32_e32 v0, v14, v0
	v_add_f32_e32 v0, v17, v0
	v_pk_mul_f32 v[18:19], v[12:13], v[12:13]
	v_add_f32_e32 v0, v16, v0
	v_add_f32_e32 v0, v19, v0
	v_pk_mul_f32 v[20:21], v[4:5], v[4:5]
	v_add_f32_e32 v0, v18, v0
	v_add_f32_e32 v0, v21, v0
	v_add_f32_e32 v0, v20, v0
	ds_bpermute_b32 v14, v48, v0
	v_mul_u32_u24_e32 v16, 0x88, v46
	v_lshlrev_b32_e32 v15, 1, v45
	v_and_b32_e32 v23, 31, v44
	v_bfe_u32 v22, v44, 5, 1
	s_waitcnt lgkmcnt(0)
	v_add_f32_e32 v0, v0, v14
	ds_bpermute_b32 v14, v42, v0
	s_waitcnt lgkmcnt(0)
	v_add_f32_e32 v0, v0, v14
	v_fmamk_f32 v0, v0, 0x3c800000, v185
	v_mul_f32_e32 v14, 0x4b800000, v0
	v_cmp_gt_f32_e32 vcc, s80, v0
	s_nop 1
	v_cndmask_b32_e32 v0, v0, v14, vcc
	v_rsq_f32_e32 v0, v0
	v_lshlrev_b32_e32 v14, 1, v16
	v_add3_u32 v16, 0, v15, v14
	v_add3_u32 v14, 0, v14, v15
	v_mul_f32_e32 v15, 0x45800000, v0
	v_cndmask_b32_e32 v0, v0, v15, vcc
	v_pk_mul_f32 v[6:7], v[6:7], v[0:1] op_sel_hi:[1,0]
	v_pk_mul_f32 v[2:3], v[2:3], v[0:1] op_sel_hi:[1,0]
	v_cvt_pk_bf16_f32 v6, v6, v7
	ds_write_b16 v16, v6
	ds_write_b16_d16_hi v14, v6 offset:272
	v_pk_mul_f32 v[6:7], v[24:25], v[0:1] op_sel_hi:[1,0]
	v_pk_mov_b32 v[2:3], v[2:3], v[2:3] op_sel:[1,0]
	v_cvt_pk_bf16_f32 v6, v6, v7
	ds_write_b16 v16, v6 offset:544
	ds_write_b16_d16_hi v14, v6 offset:816
	v_pk_mul_f32 v[6:7], v[8:9], v[0:1] op_sel_hi:[1,0]
	v_cvt_pk_bf16_f32 v2, v2, v3
	v_cvt_pk_bf16_f32 v6, v6, v7
	ds_write_b16 v16, v6 offset:1088
	ds_write_b16_d16_hi v14, v6 offset:1360
	v_pk_mul_f32 v[6:7], v[30:31], v[0:1] op_sel_hi:[1,0]
	v_ashrrev_i32_e32 v25, 7, v44
	v_cvt_pk_bf16_f32 v6, v6, v7
	ds_write_b16 v16, v6 offset:1632
	ds_write_b16_d16_hi v14, v6 offset:1904
	v_pk_mul_f32 v[6:7], v[10:11], v[0:1] op_sel_hi:[1,0]
	v_lshlrev_b32_e32 v18, 5, v25
	v_pk_mov_b32 v[6:7], v[6:7], v[6:7] op_sel:[1,0]
	v_ashrrev_i32_e32 v19, 31, v18
	v_cvt_pk_bf16_f32 v6, v6, v7
	ds_write_b16 v16, v6 offset:2176
	ds_write_b16_d16_hi v14, v6 offset:2448
	ds_write_b16 v16, v2 offset:2720
	ds_write_b16_d16_hi v14, v2 offset:2992
	v_pk_mul_f32 v[2:3], v[12:13], v[0:1] op_sel_hi:[1,0]
	v_mov_b32_e32 v6, v1
	v_pk_mov_b32 v[2:3], v[2:3], v[2:3] op_sel:[1,0]
	v_mov_b32_e32 v7, v1
	v_cvt_pk_bf16_f32 v2, v2, v3
	ds_write_b16 v16, v2 offset:3264
	ds_write_b16_d16_hi v14, v2 offset:3536
	v_pk_mul_f32 v[2:3], v[4:5], v[0:1] op_sel_hi:[1,0]
	v_mov_b32_e32 v5, v1
	v_pk_mov_b32 v[2:3], v[2:3], v[2:3] op_sel:[1,0]
	v_mov_b32_e32 v8, v1
	v_cvt_pk_bf16_f32 v0, v2, v3
	ds_write_b16 v16, v0 offset:3808
	ds_write_b16_d16_hi v14, v0 offset:4080
	v_lshl_add_u64 v[2:3], v[18:19], 0, s[54:55]
	v_lshrrev_b32_e32 v0, 1, v44
	v_or_b32_e32 v2, v2, v23
	v_and_b32_e32 v19, 32, v0
	v_lshlrev_b64 v[2:3], 8, v[2:3]
	v_or_b32_e32 v0, v19, v23
	v_mul_u32_u24_e32 v4, 0x110, v0
	v_lshl_add_u64 v[2:3], s[30:31], 0, v[2:3]
	v_lshlrev_b32_e32 v0, 4, v22
	v_lshl_add_u64 v[20:21], v[2:3], 0, v[0:1]
	v_add3_u32 v24, 0, v4, v0
	v_mov_b32_e32 v2, v1
	v_mov_b32_e32 v3, v1
	v_mov_b32_e32 v4, v1
	v_mov_b32_e32 v9, v1
	v_mov_b32_e32 v10, v1
	v_mov_b32_e32 v11, v1
	v_mov_b32_e32 v12, v1
	v_mov_b32_e32 v13, v1
	v_mov_b32_e32 v14, v1
	v_mov_b32_e32 v15, v1
	v_mov_b32_e32 v0, v1
	v_mov_b64_e32 v[16:17], v[14:15]
	v_cmp_lt_i32_e32 vcc, -1, v25
	v_mov_b64_e32 v[14:15], v[12:13]
	v_mov_b64_e32 v[12:13], v[10:11]
	v_mov_b64_e32 v[10:11], v[8:9]
	v_mov_b64_e32 v[8:9], v[6:7]
	v_mov_b64_e32 v[6:7], v[4:5]
	v_mov_b64_e32 v[4:5], v[2:3]
	v_mov_b64_e32 v[2:3], v[0:1]
	global_load_dwordx4 v[50:53], v[20:21], off
	global_load_dwordx4 v[54:57], v[20:21], off offset:32
	global_load_dwordx4 v[58:61], v[20:21], off offset:64
	global_load_dwordx4 v[62:65], v[20:21], off offset:96
	global_load_dwordx4 v[66:69], v[20:21], off offset:128
	global_load_dwordx4 v[70:73], v[20:21], off offset:160
	global_load_dwordx4 v[74:77], v[20:21], off offset:192
	global_load_dwordx4 v[78:81], v[20:21], off offset:224
	s_waitcnt lgkmcnt(0)
	s_barrier
	ds_read_b128 v[82:85], v24
	ds_read_b128 v[86:89], v24 offset:32
	ds_read_b128 v[94:97], v24 offset:64
	ds_read_b128 v[98:101], v24 offset:96
	ds_read_b128 v[102:105], v24 offset:128
	ds_read_b128 v[106:109], v24 offset:160
	ds_read_b128 v[110:113], v24 offset:192
	ds_read_b128 v[114:117], v24 offset:224
	s_lshl_b32 s6, s5, 6
	s_mov_b64 s[0:1], exec
	s_waitcnt vmcnt(6) lgkmcnt(6)
	v_mfma_f32_32x32x16_bf16 v[2:17], v[82:85], v[50:53], 0
	v_mfma_f32_32x32x16_bf16 v[2:17], v[86:89], v[54:57], v[2:17]
	v_cmp_lt_i32_e32 vcc, 0, v25
	s_cbranch_vccz .LBB0_1316
	s_waitcnt vmcnt(4) lgkmcnt(4)
	v_mfma_f32_32x32x16_bf16 v[2:17], v[94:97], v[58:61], v[2:17]
	v_mfma_f32_32x32x16_bf16 v[2:17], v[98:101], v[62:65], v[2:17]
	v_cmp_lt_i32_e32 vcc, 1, v25
	s_cbranch_vccz .LBB0_1316
	s_waitcnt vmcnt(2) lgkmcnt(2)
	v_mfma_f32_32x32x16_bf16 v[2:17], v[102:105], v[66:69], v[2:17]
	v_mfma_f32_32x32x16_bf16 v[2:17], v[106:109], v[70:73], v[2:17]
	v_cmp_lt_i32_e32 vcc, 2, v25
	s_cbranch_vccz .LBB0_1316
	s_waitcnt vmcnt(0) lgkmcnt(0)
	v_mfma_f32_32x32x16_bf16 v[2:17], v[110:113], v[74:77], v[2:17]
	v_mfma_f32_32x32x16_bf16 v[2:17], v[114:117], v[78:81], v[2:17]
	s_branch .LBB0_1316

.LBB0_1407:
	s_cmpk_gt_u32 s18, 0x17f
	s_cbranch_scc0 .LBB0_1421
	s_lshl_b32 s0, s18, 4
	v_mov_b32_e32 v44, v173
	s_and_b32 s2, s0, 0x7fffff80
	s_addk_i32 s2, 0xe800
	v_ashrrev_i32_e32 v45, 2, v44
	v_add_u32_e32 v0, s2, v45
	v_mov_b64_e32 v[2:3], s[50:51]
	s_and_b32 s3, s18, 7
	v_mad_i64_i32 v[2:3], s[0:1], v0, s84, v[2:3]
	v_lshlrev_b32_e32 v0, 4, v44
	s_lshl_b32 s54, s3, 7
	v_and_b32_e32 v46, 48, v0
	v_lshl_add_u64 v[2:3], v[2:3], 0, s[54:55]
	v_lshlrev_b32_e32 v0, 1, v46
	v_lshl_add_u64 v[2:3], v[2:3], 0, v[0:1]
	global_load_dwordx4 v[10:13], v[2:3], off offset:1040
	s_nop 0
	global_load_dwordx4 v[2:5], v[2:3], off offset:1024
	v_and_b32_e32 v30, 64, v189
	v_add_u32_e32 v47, 64, v30
	v_readlane_b32 s0, v254, 61
	s_or_b32 s0, s3, s0
	s_lshl_b32 s54, s0, 7
	s_waitcnt vmcnt(0)
	v_lshlrev_b32_e32 v7, 16, v10
	v_lshlrev_b32_e32 v9, 16, v11
	v_mul_f32_e32 v0, 0x3d372713, v7
	v_and_b32_e32 v6, 0xffff0000, v10
	v_mov_b32_e32 v14, v7
	v_mul_f32_e32 v17, 0x3d372713, v9
	v_mul_f32_e32 v0, v0, v7
	v_lshlrev_b32_e32 v30, 16, v2
	v_mul_f32_e32 v15, 0x3d372713, v6
	v_mov_b32_e32 v18, v9
	v_mul_f32_e32 v17, v17, v9
	v_fmac_f32_e32 v14, v0, v14
	v_and_b32_e32 v31, 0xffff0000, v2
	v_mul_f32_e32 v2, 0x3d372713, v30
	v_mov_b32_e32 v16, v6
	v_mul_f32_e32 v15, v15, v6
	v_fmac_f32_e32 v18, v17, v18
	v_mul_f32_e32 v0, 0xbfcc422a, v14
	v_mul_f32_e32 v2, v2, v30
	v_mov_b32_e32 v32, v30
	v_fmac_f32_e32 v16, v15, v16
	v_mul_f32_e32 v15, 0xbfcc422a, v18
	v_mul_f32_e32 v0, 0x3fb8aa3b, v0
	v_fmac_f32_e32 v32, v2, v32
	v_mul_f32_e32 v15, 0x3fb8aa3b, v15
	v_exp_f32_e32 v0, v0
	v_mul_f32_e32 v2, 0xbfcc422a, v32
	v_mul_f32_e32 v32, 0x3d372713, v31
	v_exp_f32_e32 v15, v15
	v_mul_f32_e32 v32, v32, v31
	v_mov_b32_e32 v33, v31
	v_and_b32_e32 v8, 0xffff0000, v11
	v_lshlrev_b32_e32 v11, 16, v12
	v_fmac_f32_e32 v33, v32, v33
	v_mul_f32_e32 v21, 0x3d372713, v11
	v_mul_f32_e32 v2, 0x3fb8aa3b, v2
	v_mul_f32_e32 v32, 0xbfcc422a, v33
	v_mov_b32_e32 v22, v11
	v_mul_f32_e32 v21, v21, v11
	v_add_f32_e32 v0, 1.0, v0
	v_exp_f32_e32 v2, v2
	v_mul_f32_e32 v32, 0x3fb8aa3b, v32
	v_fmac_f32_e32 v22, v21, v22
	v_add_f32_e32 v21, 1.0, v15
	v_rcp_f32_e32 v15, v0
	v_xor_b32_e32 v0, 1, v189
	v_exp_f32_e32 v32, v32
	v_cmp_lt_i32_e32 vcc, v0, v47
	v_and_b32_e32 v33, 0xffff0000, v3
	v_mov_b32_e32 v35, v33
	v_cndmask_b32_e32 v0, v189, v0, vcc
	v_lshlrev_b32_e32 v48, 2, v0
	v_add_f32_e32 v0, 1.0, v2
	v_rcp_f32_e32 v2, v0
	v_add_f32_e32 v0, 1.0, v32
	v_lshlrev_b32_e32 v32, 16, v3
	v_mul_f32_e32 v3, 0x3d372713, v32
	v_mul_f32_e32 v3, v3, v32
	v_mov_b32_e32 v34, v32
	v_fmac_f32_e32 v34, v3, v34
	v_mul_f32_e32 v3, 0xbfcc422a, v34
	v_mul_f32_e32 v3, 0x3fb8aa3b, v3
	v_exp_f32_e32 v34, v3
	v_mul_f32_e32 v3, 0x3d372713, v33
	v_mul_f32_e32 v3, v3, v33
	v_fmac_f32_e32 v35, v3, v35
	v_mul_f32_e32 v3, 0xbfcc422a, v35
	v_mul_f32_e32 v3, 0x3fb8aa3b, v3
	v_exp_f32_e32 v35, v3
	v_rcp_f32_e32 v3, v0
	v_add_f32_e32 v0, 1.0, v34
	v_rcp_f32_e32 v34, v0
	v_add_f32_e32 v0, 1.0, v35
	v_rcp_f32_e32 v35, v0
	v_pk_mul_f32 v[36:37], v[2:3], v[30:31]
	v_lshlrev_b32_e32 v38, 16, v4
	v_add_f32_e32 v0, 0, v36
	v_add_f32_e32 v0, v37, v0
	v_pk_mul_f32 v[36:37], v[34:35], v[32:33]
	v_and_b32_e32 v39, 0xffff0000, v4
	v_mul_f32_e32 v4, 0x3d372713, v38
	v_add_f32_e32 v0, v36, v0
	v_mul_f32_e32 v4, v4, v38
	v_mov_b32_e32 v36, v38
	v_fmac_f32_e32 v36, v4, v36
	v_mul_f32_e32 v4, 0xbfcc422a, v36
	v_mul_f32_e32 v36, 0x3d372713, v39
	v_mul_f32_e32 v36, v36, v39
	v_mov_b32_e32 v40, v39
	v_fmac_f32_e32 v40, v36, v40
	v_mul_f32_e32 v36, 0xbfcc422a, v40
	v_mul_f32_e32 v36, 0x3fb8aa3b, v36
	v_exp_f32_e32 v36, v36
	v_add_f32_e32 v0, v37, v0
	v_and_b32_e32 v37, 0xffff0000, v5
	v_mov_b32_e32 v42, v37
	v_add_f32_e32 v40, 1.0, v36
	v_lshlrev_b32_e32 v36, 16, v5
	v_mul_f32_e32 v5, 0x3d372713, v36
	v_mul_f32_e32 v5, v5, v36
	v_mov_b32_e32 v41, v36
	v_fmac_f32_e32 v41, v5, v41
	v_mul_f32_e32 v5, 0xbfcc422a, v41
	v_mul_f32_e32 v5, 0x3fb8aa3b, v5
	v_exp_f32_e32 v41, v5
	v_mul_f32_e32 v5, 0x3d372713, v37
	v_mul_f32_e32 v5, v5, v37
	v_mul_f32_e32 v4, 0x3fb8aa3b, v4
	v_fmac_f32_e32 v42, v5, v42
	v_exp_f32_e32 v4, v4
	v_mul_f32_e32 v5, 0xbfcc422a, v42
	v_mul_f32_e32 v19, 0x3d372713, v8
	v_mul_f32_e32 v5, 0x3fb8aa3b, v5
	v_and_b32_e32 v10, 0xffff0000, v12
	v_and_b32_e32 v12, 0xffff0000, v13
	v_lshlrev_b32_e32 v13, 16, v13
	v_mov_b32_e32 v20, v8
	v_mul_f32_e32 v19, v19, v8
	v_mul_f32_e32 v14, 0xbfcc422a, v16
	v_exp_f32_e32 v42, v5
	v_mul_f32_e32 v23, 0x3d372713, v10
	v_mul_f32_e32 v25, 0x3d372713, v13
	v_fmac_f32_e32 v20, v19, v20
	v_mul_f32_e32 v14, 0x3fb8aa3b, v14
	v_mov_b32_e32 v24, v10
	v_mov_b32_e32 v26, v13
	v_mul_f32_e32 v23, v23, v10
	v_mul_f32_e32 v25, v25, v13
	v_mul_f32_e32 v16, 0xbfcc422a, v20
	v_exp_f32_e32 v14, v14
	v_add_f32_e32 v4, 1.0, v4
	v_mul_f32_e32 v27, 0x3d372713, v12
	v_fmac_f32_e32 v24, v23, v24
	v_fmac_f32_e32 v26, v25, v26
	v_mul_f32_e32 v17, 0xbfcc422a, v22
	v_mul_f32_e32 v16, 0x3fb8aa3b, v16
	v_rcp_f32_e32 v4, v4
	v_rcp_f32_e32 v5, v40
	v_mov_b32_e32 v28, v12
	v_mul_f32_e32 v27, v27, v12
	v_mul_f32_e32 v18, 0xbfcc422a, v24
	v_mul_f32_e32 v19, 0xbfcc422a, v26
	v_mul_f32_e32 v17, 0x3fb8aa3b, v17
	v_exp_f32_e32 v16, v16
	v_add_f32_e32 v40, 1.0, v41
	v_add_f32_e32 v41, 1.0, v42
	v_fmac_f32_e32 v28, v27, v28
	v_mul_f32_e32 v18, 0x3fb8aa3b, v18
	v_mul_f32_e32 v19, 0x3fb8aa3b, v19
	v_exp_f32_e32 v17, v17
	v_rcp_f32_e32 v40, v40
	v_rcp_f32_e32 v41, v41
	v_mul_f32_e32 v20, 0xbfcc422a, v28
	v_exp_f32_e32 v18, v18
	v_exp_f32_e32 v19, v19
	v_add_f32_e32 v14, 1.0, v14
	v_mul_f32_e32 v20, 0x3fb8aa3b, v20
	v_rcp_f32_e32 v14, v14
	v_pk_mul_f32 v[42:43], v[4:5], v[38:39]
	v_exp_f32_e32 v20, v20
	v_add_f32_e32 v16, 1.0, v16
	v_add_f32_e32 v0, v42, v0
	v_add_f32_e32 v22, 1.0, v17
	v_rcp_f32_e32 v17, v21
	v_rcp_f32_e32 v16, v16
	v_add_f32_e32 v0, v43, v0
	v_pk_mul_f32 v[42:43], v[40:41], v[36:37]
	v_add_f32_e32 v18, 1.0, v18
	v_add_f32_e32 v23, 1.0, v19
	v_add_f32_e32 v0, v42, v0
	v_rcp_f32_e32 v19, v22
	v_rcp_f32_e32 v18, v18
	v_rcp_f32_e32 v21, v23
	v_pk_mul_f32 v[22:23], v[14:15], v[6:7]
	v_add_f32_e32 v0, v43, v0
	v_add_f32_e32 v20, 1.0, v20
	v_add_f32_e32 v0, v23, v0
	v_rcp_f32_e32 v20, v20
	v_pk_mul_f32 v[24:25], v[16:17], v[8:9]
	v_add_f32_e32 v0, v22, v0
	v_add_f32_e32 v0, v25, v0
	v_pk_mul_f32 v[26:27], v[18:19], v[10:11]
	v_add_f32_e32 v0, v24, v0
	v_add_f32_e32 v0, v27, v0
	v_pk_mul_f32 v[28:29], v[20:21], v[12:13]
	v_add_f32_e32 v0, v26, v0
	v_add_f32_e32 v0, v29, v0
	v_add_f32_e32 v0, v28, v0
	ds_bpermute_b32 v22, v48, v0
	v_xor_b32_e32 v23, 2, v189
	v_cmp_lt_i32_e32 vcc, v23, v47
	s_waitcnt lgkmcnt(0)
	v_add_f32_e32 v0, v0, v22
	v_cndmask_b32_e32 v23, v189, v23, vcc
	v_lshlrev_b32_e32 v42, 2, v23
	ds_bpermute_b32 v22, v42, v0
	s_waitcnt lgkmcnt(0)
	v_add_f32_e32 v0, v0, v22
	v_mul_f32_e32 v0, 0x3c800000, v0
	v_pk_fma_f32 v[2:3], v[2:3], v[30:31], v[0:1] op_sel_hi:[1,1,0] neg_lo:[0,0,1] neg_hi:[0,0,1]
	v_pk_fma_f32 v[24:25], v[34:35], v[32:33], v[0:1] op_sel_hi:[1,1,0] neg_lo:[0,0,1] neg_hi:[0,0,1]
	v_pk_mul_f32 v[22:23], v[2:3], v[2:3]
	v_pk_mul_f32 v[26:27], v[24:25], v[24:25]
	v_pk_fma_f32 v[4:5], v[4:5], v[38:39], v[0:1] op_sel_hi:[1,1,0] neg_lo:[0,0,1] neg_hi:[0,0,1]
	v_pk_fma_f32 v[30:31], v[40:41], v[36:37], v[0:1] op_sel_hi:[1,1,0] neg_lo:[0,0,1] neg_hi:[0,0,1]
	v_pk_fma_f32 v[10:11], v[18:19], v[10:11], v[0:1] op_sel_hi:[1,1,0] neg_lo:[0,0,1] neg_hi:[0,0,1]
	v_pk_fma_f32 v[12:13], v[20:21], v[12:13], v[0:1] op_sel_hi:[1,1,0] neg_lo:[0,0,1] neg_hi:[0,0,1]
	v_pk_fma_f32 v[6:7], v[14:15], v[6:7], v[0:1] op_sel_hi:[1,1,0] neg_lo:[0,0,1] neg_hi:[0,0,1]
	v_pk_fma_f32 v[8:9], v[16:17], v[8:9], v[0:1] op_sel_hi:[1,1,0] neg_lo:[0,0,1] neg_hi:[0,0,1]
	v_add_f32_e32 v0, v22, v23
	v_add_f32_e32 v0, v26, v0
	v_pk_mul_f32 v[28:29], v[4:5], v[4:5]
	v_add_f32_e32 v0, v27, v0
	v_add_f32_e32 v0, v28, v0
	v_pk_mul_f32 v[32:33], v[30:31], v[30:31]
	v_add_f32_e32 v0, v29, v0
	v_add_f32_e32 v0, v32, v0
	v_pk_mul_f32 v[14:15], v[6:7], v[6:7]
	v_add_f32_e32 v0, v33, v0
	v_add_f32_e32 v0, v15, v0
	v_pk_mul_f32 v[16:17], v[8:9], v[8:9]
	v_add_f32_e32 v0, v14, v0
	v_add_f32_e32 v0, v17, v0
	v_pk_mul_f32 v[18:19], v[10:11], v[10:11]
	v_add_f32_e32 v0, v16, v0
	v_add_f32_e32 v0, v19, v0
	v_pk_mul_f32 v[20:21], v[12:13], v[12:13]
	v_add_f32_e32 v0, v18, v0
	v_add_f32_e32 v0, v21, v0
	v_add_f32_e32 v0, v20, v0
	ds_bpermute_b32 v14, v48, v0
	v_mul_u32_u24_e32 v16, 0x88, v46
	v_lshlrev_b32_e32 v15, 1, v45
	v_and_b32_e32 v23, 31, v44
	v_bfe_u32 v22, v44, 5, 1
	s_waitcnt lgkmcnt(0)
	v_add_f32_e32 v0, v0, v14
	ds_bpermute_b32 v14, v42, v0
	s_waitcnt lgkmcnt(0)
	v_add_f32_e32 v0, v0, v14
	v_fmamk_f32 v0, v0, 0x3c800000, v185
	v_mul_f32_e32 v14, 0x4b800000, v0
	v_cmp_gt_f32_e32 vcc, s80, v0
	s_nop 1
	v_cndmask_b32_e32 v0, v0, v14, vcc
	v_rsq_f32_e32 v0, v0
	v_lshlrev_b32_e32 v14, 1, v16
	v_add3_u32 v16, 0, v15, v14
	v_add3_u32 v14, 0, v14, v15
	v_mul_f32_e32 v15, 0x45800000, v0
	v_cndmask_b32_e32 v0, v0, v15, vcc
	v_pk_mul_f32 v[2:3], v[2:3], v[0:1] op_sel_hi:[1,0]
	v_mov_b32_e32 v15, v1
	v_cvt_pk_bf16_f32 v2, v2, v3
	ds_write_b16 v16, v2
	ds_write_b16_d16_hi v14, v2 offset:272
	v_pk_mul_f32 v[2:3], v[24:25], v[0:1] op_sel_hi:[1,0]
	v_ashrrev_i32_e32 v25, 7, v44
	v_cvt_pk_bf16_f32 v2, v2, v3
	ds_write_b16 v16, v2 offset:544
	ds_write_b16_d16_hi v14, v2 offset:816
	v_pk_mul_f32 v[2:3], v[4:5], v[0:1] op_sel_hi:[1,0]
	v_lshlrev_b32_e32 v18, 5, v25
	v_cvt_pk_bf16_f32 v2, v2, v3
	ds_write_b16 v16, v2 offset:1088
	ds_write_b16_d16_hi v14, v2 offset:1360
	v_pk_mul_f32 v[2:3], v[30:31], v[0:1] op_sel_hi:[1,0]
	v_ashrrev_i32_e32 v19, 31, v18
	v_cvt_pk_bf16_f32 v2, v2, v3
	ds_write_b16 v16, v2 offset:1632
	ds_write_b16_d16_hi v14, v2 offset:1904
	v_pk_mul_f32 v[2:3], v[6:7], v[0:1] op_sel_hi:[1,0]
	v_mov_b32_e32 v5, v1
	v_pk_mov_b32 v[2:3], v[2:3], v[2:3] op_sel:[1,0]
	v_mov_b32_e32 v6, v1
	v_cvt_pk_bf16_f32 v2, v2, v3
	ds_write_b16 v16, v2 offset:2176
	ds_write_b16_d16_hi v14, v2 offset:2448
	v_pk_mul_f32 v[2:3], v[8:9], v[0:1] op_sel_hi:[1,0]
	v_mov_b32_e32 v7, v1
	v_pk_mov_b32 v[2:3], v[2:3], v[2:3] op_sel:[1,0]
	v_mov_b32_e32 v8, v1
	v_cvt_pk_bf16_f32 v2, v2, v3
	ds_write_b16 v16, v2 offset:2720
	ds_write_b16_d16_hi v14, v2 offset:2992
	v_pk_mul_f32 v[2:3], v[10:11], v[0:1] op_sel_hi:[1,0]
	v_mov_b32_e32 v9, v1
	v_pk_mov_b32 v[2:3], v[2:3], v[2:3] op_sel:[1,0]
	v_mov_b32_e32 v10, v1
	v_cvt_pk_bf16_f32 v2, v2, v3
	ds_write_b16 v16, v2 offset:3264
	ds_write_b16_d16_hi v14, v2 offset:3536
	v_pk_mul_f32 v[2:3], v[12:13], v[0:1] op_sel_hi:[1,0]
	v_mov_b32_e32 v11, v1
	v_pk_mov_b32 v[2:3], v[2:3], v[2:3] op_sel:[1,0]
	v_mov_b32_e32 v12, v1
	v_cvt_pk_bf16_f32 v0, v2, v3
	ds_write_b16 v16, v0 offset:3808
	ds_write_b16_d16_hi v14, v0 offset:4080
	v_lshl_add_u64 v[2:3], v[18:19], 0, s[54:55]
	v_lshrrev_b32_e32 v0, 1, v44
	v_or_b32_e32 v2, v2, v23
	v_and_b32_e32 v19, 32, v0
	v_lshlrev_b64 v[2:3], 8, v[2:3]
	v_or_b32_e32 v0, v19, v23
	v_mul_u32_u24_e32 v4, 0x110, v0
	v_lshl_add_u64 v[2:3], s[30:31], 0, v[2:3]
	v_lshlrev_b32_e32 v0, 4, v22
	v_lshl_add_u64 v[20:21], v[2:3], 0, v[0:1]
	v_add3_u32 v24, 0, v4, v0
	v_mov_b32_e32 v2, v1
	v_mov_b32_e32 v3, v1
	v_mov_b32_e32 v4, v1
	v_mov_b32_e32 v13, v1
	v_mov_b32_e32 v14, v1
	v_mov_b32_e32 v0, v1
	v_mov_b64_e32 v[16:17], v[14:15]
	v_cmp_lt_i32_e32 vcc, -1, v25
	v_mov_b64_e32 v[14:15], v[12:13]
	v_mov_b64_e32 v[12:13], v[10:11]
	v_mov_b64_e32 v[10:11], v[8:9]
	v_mov_b64_e32 v[8:9], v[6:7]
	v_mov_b64_e32 v[6:7], v[4:5]
	v_mov_b64_e32 v[4:5], v[2:3]
	v_mov_b64_e32 v[2:3], v[0:1]
	global_load_dwordx4 v[50:53], v[20:21], off
	global_load_dwordx4 v[54:57], v[20:21], off offset:32
	global_load_dwordx4 v[58:61], v[20:21], off offset:64
	global_load_dwordx4 v[62:65], v[20:21], off offset:96
	global_load_dwordx4 v[66:69], v[20:21], off offset:128
	global_load_dwordx4 v[70:73], v[20:21], off offset:160
	global_load_dwordx4 v[74:77], v[20:21], off offset:192
	global_load_dwordx4 v[78:81], v[20:21], off offset:224
	s_waitcnt lgkmcnt(0)
	s_barrier
	ds_read_b128 v[82:85], v24
	ds_read_b128 v[86:89], v24 offset:32
	ds_read_b128 v[94:97], v24 offset:64
	ds_read_b128 v[98:101], v24 offset:96
	ds_read_b128 v[102:105], v24 offset:128
	ds_read_b128 v[106:109], v24 offset:160
	ds_read_b128 v[110:113], v24 offset:192
	ds_read_b128 v[114:117], v24 offset:224
	s_lshl_b32 s3, s3, 6
	s_mov_b64 s[0:1], exec
	s_waitcnt vmcnt(6) lgkmcnt(6)
	v_mfma_f32_32x32x16_bf16 v[2:17], v[82:85], v[50:53], 0
	v_mfma_f32_32x32x16_bf16 v[2:17], v[86:89], v[54:57], v[2:17]
	v_cmp_lt_i32_e32 vcc, 0, v25
	s_cbranch_vccz .LBB0_1420
	s_waitcnt vmcnt(4) lgkmcnt(4)
	v_mfma_f32_32x32x16_bf16 v[2:17], v[94:97], v[58:61], v[2:17]
	v_mfma_f32_32x32x16_bf16 v[2:17], v[98:101], v[62:65], v[2:17]
	v_cmp_lt_i32_e32 vcc, 1, v25
	s_cbranch_vccz .LBB0_1420
	s_waitcnt vmcnt(2) lgkmcnt(2)
	v_mfma_f32_32x32x16_bf16 v[2:17], v[102:105], v[66:69], v[2:17]
	v_mfma_f32_32x32x16_bf16 v[2:17], v[106:109], v[70:73], v[2:17]
	v_cmp_lt_i32_e32 vcc, 2, v25
	s_cbranch_vccz .LBB0_1420
	s_waitcnt vmcnt(0) lgkmcnt(0)
	v_mfma_f32_32x32x16_bf16 v[2:17], v[110:113], v[74:77], v[2:17]
	v_mfma_f32_32x32x16_bf16 v[2:17], v[114:117], v[78:81], v[2:17]

.LBB0_1472:
	s_and_b64 vcc, exec, s[0:1]
	s_cbranch_vccz .LBB0_1403
	v_mov_b32_e32 v0, 0
	s_and_saveexec_b64 s[0:1], s[6:7]
	s_cbranch_execz .LBB0_1402
	v_lshl_add_u32 v2, v8, 9, v18
	v_ashrrev_i32_e32 v3, 31, v2
	v_lshlrev_b64 v[2:3], 2, v[2:3]
	v_lshl_add_u64 v[6:7], s[8:9], 0, v[2:3]
	v_lshl_add_u64 v[2:3], s[10:11], 0, v[2:3]
	global_load_dword v6, v[6:7], off
	v_add_u32_e32 v0, v17, v12
	global_load_dword v7, v[2:3], off
	ds_read2_b32 v[2:3], v0 offset1:32
	s_waitcnt vmcnt(0) lgkmcnt(0)
	v_pk_mul_f32 v[10:11], v[6:7], v[2:3]
	s_nop 0
	v_sub_f32_e32 v0, v10, v11
	v_mov_b32_e32 v10, v7
	v_mov_b32_e32 v11, v6
	v_pk_mul_f32 v[2:3], v[10:11], v[2:3]
	s_nop 0
	v_add_f32_e32 v2, v2, v3
	v_cndmask_b32_e64 v0, v2, v0, s[2:3]
	v_cvt_pk_bf16_f32 v0, v0, s0
	s_branch .LBB0_1402
.LBB0_1479:
	s_mov_b64 s[0:1], 0
